# LN stats exchange: redundant agent invalidate dropped (slots read by sc1 loads); phase 5 sample out-proj epilogue operand loads hoisted above its barrier
# speedup vs baseline: 1.0170x; 1.0038x over previous
.LBB0_923:
	s_add_u32 s24, s68, 0x14400000
	s_addc_u32 s25, s69, 0
	s_cmp_lt_i32 s92, 6
	s_cselect_b64 s[0:1], -1, 0
	s_cmp_gt_i32 s93, 5
	s_cselect_b64 s[2:3], -1, 0
	s_and_b64 s[0:1], s[0:1], s[2:3]
	s_andn2_b64 vcc, exec, s[0:1]
	s_cbranch_vccnz .LBB0_1039
	s_waitcnt vmcnt(0)
	v_mov_b32_e32 v5, v0
	s_lshl_b32 s2, s12, 4
	s_and_b32 s2, s2, 0x70
	v_and_b32_e32 v8, 15, v5
	v_readfirstlane_b32 s0, v5
	s_ashr_i32 s1, s0, 6
	v_or_b32_e32 v4, s2, v8
	s_lshl_b32 s2, s12, 2
	s_andn2_b32 s2, s2, 31
	s_lshl_b32 s4, s1, 7
	v_or_b32_e32 v8, s2, v8
	s_ashr_i32 s5, s4, 31
	s_lshl_b64 s[6:7], s[4:5], 1
	v_ashrrev_i32_e32 v9, 31, v8
	s_waitcnt lgkmcnt(0)
	v_mov_b32_e32 v3, 0
	v_lshlrev_b32_e32 v2, 11, v4
	s_add_u32 s6, s35, s6
	v_lshlrev_b64 v[12:13], 11, v[8:9]
	v_or_b32_e32 v8, 16, v8
	v_lshl_add_u64 v[6:7], s[56:57], 0, v[2:3]
	s_addc_u32 s7, s90, s7
	v_and_b32_e32 v2, 48, v5
	v_ashrrev_i32_e32 v9, 31, v8
	v_bfe_u32 v1, v5, 4, 2
	v_lshl_add_u64 v[10:11], s[6:7], 0, v[2:3]
	v_lshlrev_b64 v[8:9], 11, v[8:9]
	v_lshl_add_u64 v[40:41], v[10:11], 0, v[8:9]
	v_lshl_or_b32 v8, v1, 3, s4
	v_lshl_add_u64 v[38:39], v[10:11], 0, v[12:13]
	v_ashrrev_i32_e32 v9, 31, v8
	v_lshl_add_u64 v[22:23], v[8:9], 1, v[6:7]
	s_cmp_gt_i32 s1, 1
	s_cbranch_scc1 .Lpr5_noepi
	s_lshl_b32 s8, s1, 4
	s_add_i32 s8, s8, s2
	v_lshl_or_b32 v216, v1, 2, s8
	v_lshlrev_b32_e32 v218, 10, v4
	v_mov_b32_e32 v219, 0
	v_ashrrev_i32_e32 v217, 31, v216
	v_mul_u32_u24_e32 v220, 0x1800, v4
	v_lshl_add_u64 v[222:223], v[216:217], 0, v[218:219]
	v_lshlrev_b32_e32 v218, 2, v220
	v_lshl_add_u64 v[220:221], s[70:71], 0, v[218:219]
	v_lshl_add_u64 v[216:217], v[216:217], 2, v[220:221]
	s_mov_b32 s8, 0x32000
	v_add_co_u32_e32 v216, vcc, s8, v216
	v_lshlrev_b64 v[222:223], 2, v[222:223]
	s_nop 0
	v_addc_co_u32_e32 v217, vcc, 0, v217, vcc
	global_load_dwordx4 v[200:203], v[216:217], off
	v_readlane_b32 s38, v245, 4
	v_readlane_b32 s39, v245, 5
	s_nop 0
	v_lshl_add_u64 v[220:221], s[38:39], 0, v[222:223]
	global_load_dwordx4 v[204:207], v[220:221], off
.Lpr5_noepi:
	global_load_dwordx4 v[6:9], v[38:39], off
	s_brev_b32 s3, 64
	v_add_co_u32_e32 v10, vcc, s3, v22
	s_mov_b64 s[4:5], 0x2000000
	s_nop 0
	v_addc_co_u32_e32 v11, vcc, 0, v23, vcc
	global_load_dwordx4 v[10:13], v[10:11], off
	s_nop 0
	global_load_dwordx4 v[14:17], v[40:41], off
	global_load_dwordx4 v[18:21], v[38:39], off offset:64
	v_lshl_add_u64 v[42:43], v[22:23], 0, s[4:5]
	global_load_dwordx4 v[22:25], v[42:43], off offset:64
	global_load_dwordx4 v[26:29], v[40:41], off offset:64
	global_load_dwordx4 v[30:33], v[42:43], off offset:192
	global_load_dwordx4 v[34:37], v[38:39], off offset:128
	s_lshl_b32 s3, s1, 11
	v_and_b32_e32 v5, 63, v5
	s_add_i32 s3, s3, 0
	v_lshl_add_u32 v2, v5, 4, s3
	s_cmp_gt_i32 s1, 1
	s_waitcnt vmcnt(6)
	v_mfma_f32_16x16x32_bf16 v[6:9], v[6:9], v[10:13], 0
	s_waitcnt vmcnt(5)
	v_mfma_f32_16x16x32_bf16 v[10:13], v[14:17], v[10:13], 0
	global_load_dwordx4 v[14:17], v[42:43], off offset:128
	s_waitcnt vmcnt(4)
	v_mfma_f32_16x16x32_bf16 v[6:9], v[18:21], v[22:25], v[6:9]
	global_load_dwordx4 v[18:21], v[40:41], off offset:128
	s_waitcnt vmcnt(4)
	v_mfma_f32_16x16x32_bf16 v[10:13], v[26:29], v[22:25], v[10:13]
	global_load_dwordx4 v[22:25], v[38:39], off offset:192
	global_load_dwordx4 v[26:29], v[40:41], off offset:192
	s_waitcnt vmcnt(3)
	v_mfma_f32_16x16x32_bf16 v[6:9], v[34:37], v[14:17], v[6:9]
	s_waitcnt vmcnt(2)
	v_mfma_f32_16x16x32_bf16 v[10:13], v[18:21], v[14:17], v[10:13]
	s_waitcnt vmcnt(1)
	v_mfma_f32_16x16x32_bf16 v[6:9], v[22:25], v[30:33], v[6:9]
	s_waitcnt vmcnt(0)
	v_mfma_f32_16x16x32_bf16 v[10:13], v[26:29], v[30:33], v[10:13]
	s_nop 5
	ds_write_b128 v2, v[6:9]
	s_nop 0
	ds_write_b128 v2, v[10:13] offset:1024
	s_waitcnt lgkmcnt(0)
	s_barrier
	s_cbranch_scc1 .LBB0_926
	s_lshl_b32 s1, s1, 4
	s_add_i32 s1, s1, s2
	v_lshl_or_b32 v6, v1, 2, s1
	v_lshlrev_b32_e32 v2, 10, v4
	v_ashrrev_i32_e32 v7, 31, v6
	v_mul_u32_u24_e32 v1, 0x1800, v4
	v_lshl_add_u64 v[10:11], v[6:7], 0, v[2:3]
	v_lshlrev_b32_e32 v2, 2, v1
	v_lshl_add_u64 v[8:9], s[70:71], 0, v[2:3]
	v_lshl_add_u64 v[6:7], v[6:7], 2, v[8:9]
	s_mov_b32 s1, 0x32000
	v_add_co_u32_e32 v6, vcc, s1, v6
	v_readlane_b32 s36, v245, 2
	s_nop 0
	v_addc_co_u32_e32 v7, vcc, 0, v7, vcc
	v_mov_b32_e32 v6, v200
	v_mov_b32_e32 v7, v201
	v_mov_b32_e32 v8, v202
	v_mov_b32_e32 v9, v203
	v_lshlrev_b64 v[46:47], 2, v[10:11]
	v_readlane_b32 s38, v245, 4
	v_readlane_b32 s39, v245, 5
	s_and_b32 s1, s0, 0xfffffc0
	s_lshl_b32 s1, s1, 4
	v_lshl_add_u64 v[10:11], s[38:39], 0, v[46:47]
	v_mov_b32_e32 v10, v204
	v_mov_b32_e32 v11, v205
	v_mov_b32_e32 v12, v206
	v_mov_b32_e32 v13, v207
	s_add_i32 s1, s1, 0
	v_lshl_add_u32 v1, v5, 4, s1
	ds_read_b128 v[14:17], v1
	ds_read_b128 v[18:21], v1 offset:2048
	ds_read_b128 v[22:25], v1 offset:4096
	ds_read_b128 v[26:29], v1 offset:6144
	ds_read_b128 v[30:33], v1 offset:8192
	ds_read_b128 v[34:37], v1 offset:10240
	ds_read_b128 v[38:41], v1 offset:12288
	ds_read_b128 v[42:45], v1 offset:14336
	s_waitcnt lgkmcnt(6)
	v_pk_add_f32 v[4:5], v[16:17], v[20:21]
	v_pk_add_f32 v[14:15], v[14:15], v[18:19]
	s_waitcnt lgkmcnt(5)
	v_pk_add_f32 v[4:5], v[4:5], v[24:25]
	v_pk_add_f32 v[14:15], v[14:15], v[22:23]
	s_waitcnt lgkmcnt(4)
	v_pk_add_f32 v[4:5], v[4:5], v[28:29]
	v_pk_add_f32 v[14:15], v[14:15], v[26:27]
	s_waitcnt lgkmcnt(3)
	v_pk_add_f32 v[4:5], v[4:5], v[32:33]
	v_pk_add_f32 v[14:15], v[14:15], v[30:31]
	s_waitcnt lgkmcnt(2)
	v_pk_add_f32 v[4:5], v[4:5], v[36:37]
	v_pk_add_f32 v[14:15], v[14:15], v[34:35]
	s_waitcnt lgkmcnt(1)
	v_pk_add_f32 v[4:5], v[4:5], v[40:41]
	v_pk_add_f32 v[14:15], v[14:15], v[38:39]
	v_lshl_add_u64 v[46:47], s[68:69], 0, v[46:47]
	s_waitcnt lgkmcnt(0)
	v_pk_add_f32 v[4:5], v[4:5], v[44:45]
	v_pk_add_f32 v[14:15], v[14:15], v[42:43]
	s_mov_b32 s0, 0x3f9837f0
	v_add_co_u32_e32 v46, vcc, 0x14000000, v46
	v_readlane_b32 s37, v245, 3
	s_nop 0
	v_addc_co_u32_e32 v47, vcc, 0, v47, vcc
	v_readlane_b32 s40, v245, 6
	v_readlane_b32 s41, v245, 7
	v_readlane_b32 s42, v245, 8
	v_readlane_b32 s43, v245, 9
	v_readlane_b32 s44, v245, 10
	v_readlane_b32 s45, v245, 11
	v_readlane_b32 s46, v245, 12
	v_readlane_b32 s47, v245, 13
	v_readlane_b32 s48, v245, 14
	v_readlane_b32 s49, v245, 15
	v_readlane_b32 s50, v245, 16
	v_readlane_b32 s51, v245, 17
	s_waitcnt vmcnt(1)
	v_pk_add_f32 v[8:9], v[8:9], 1.0 op_sel_hi:[1,0]
	v_pk_add_f32 v[6:7], v[6:7], 1.0 op_sel_hi:[1,0]
	v_pk_mul_f32 v[4:5], v[4:5], v[8:9]
	v_pk_mul_f32 v[8:9], v[14:15], v[6:7]
	s_waitcnt vmcnt(0)
	v_pk_fma_f32 v[6:7], v[12:13], s[0:1], v[4:5] op_sel_hi:[1,0,1]
	v_pk_fma_f32 v[4:5], v[10:11], s[0:1], v[8:9] op_sel_hi:[1,0,1]
	global_store_dwordx4 v[46:47], v[4:7], off

.LBB0_979:
	s_waitcnt vmcnt(0)
	s_and_b64 exec, exec, s[2:3]
	v_cndmask_b32_e64 v136, 0, 1, s[8:9]
	v_mov_b32_e32 v137, 0
	ds_write_b32 v137, v136 offset:10240

.LBB0_1191:
	s_waitcnt vmcnt(0)
	s_and_b64 exec, exec, s[2:3]
	v_cndmask_b32_e64 v132, 0, 1, s[8:9]
	v_mov_b32_e32 v133, 0
	ds_write_b32 v133, v132 offset:10240
